# adaLN GEMM epilogue (f32 out + bias): the four bias quads of a row group are requested together instead of load-wait-add-store four times
# baseline (speedup 1.0000x reference)
; DI void gemm_epilogue(const GemmJob& J, const f32x4 (&acc)[2][2][4][2], const pg8::Unit& u, int wr, int wc, int fr, int fq) {
;     ...
;     if (J.mode == 0) {
;         float* C = (float*)J.o1; const int col0 = u.pn * 256 + wc * 32 + 4 * fq;
; #pragma unroll
;         for (int ai = 0; ai < 2; ++ai)
; #pragma unroll
;             for (int m = 0; m < 4; ++m) { const int row = rloc0 + ai * 128 + m * 16;
;                 if (row < J.flag) {
; #pragma unroll
;                     for (int bj = 0; bj < 2; ++bj)
; #pragma unroll
;                         for (int n = 0; n < 2; ++n) { const int col = col0 + bj * 128 + n * 16; const f32x4 b = *(const f32x4*)(J.f1 + col);
;                             *(f32x4*)(C + (size_t)row * J.ld1 + col) = acc[ai][bj][m][n] + b; } }
;                 asm volatile("" ::: "memory"); }
.LBB0_135:
	s_andn2_b64 vcc, exec, s[42:43]
	s_cbranch_vccnz .LBB0_84
	s_cmp_eq_u32 s74, 1
	s_mov_b64 s[42:43], -1
	s_cbranch_scc1 .LBB0_154
	v_lshl_or_b32 v130, s84, 8, v216
	v_cmp_lt_i32_e32 vcc, v218, v171
	v_ashrrev_i32_e32 v131, 31, v130
	s_and_saveexec_b64 s[42:43], vcc
	s_cbranch_execz .LBB0_139
	v_lshlrev_b64 v[136:137], 2, v[130:131]
	v_lshl_add_u64 v[138:139], s[12:13], 0, v[136:137]
	global_load_dwordx4 v[132:135], v[138:139], off
	global_load_dwordx4 v[144:147], v[138:139], off offset:64
	global_load_dwordx4 v[148:151], v[138:139], off offset:512
	global_load_dwordx4 v[152:155], v[138:139], off offset:576
	v_mad_u64_u32 v[140:141], s[30:31], v218, s27, 0
	v_ashrrev_i32_e32 v143, 31, v218
	v_mov_b32_e32 v142, v141
	v_mad_u64_u32 v[142:143], s[30:31], v143, s27, v[142:143]
	v_mov_b32_e32 v141, v142
	v_lshl_add_u64 v[140:141], v[140:141], 2, s[54:55]
	v_lshl_add_u64 v[136:137], v[140:141], 0, v[136:137]
	s_waitcnt vmcnt(0)
	v_pk_add_f32 v[134:135], v[128:129], v[134:135]
	v_pk_add_f32 v[132:133], v[126:127], v[132:133]
	global_store_dwordx4 v[136:137], v[132:135], off
	v_pk_add_f32 v[146:147], v[124:125], v[146:147]
	v_pk_add_f32 v[144:145], v[122:123], v[144:145]
	global_store_dwordx4 v[136:137], v[144:147], off offset:64
	v_pk_add_f32 v[150:151], v[112:113], v[150:151]
	v_pk_add_f32 v[148:149], v[110:111], v[148:149]
	global_store_dwordx4 v[136:137], v[148:151], off offset:512
	v_pk_add_f32 v[154:155], v[108:109], v[154:155]
	v_pk_add_f32 v[152:153], v[106:107], v[152:153]
	global_store_dwordx4 v[136:137], v[152:155], off offset:576
.LBB0_139:
	s_or_b64 exec, exec, s[42:43]
	s_nop 0
	v_or_b32_e32 v132, 16, v218
	v_cmp_lt_i32_e32 vcc, v132, v171
	s_and_saveexec_b64 s[42:43], vcc
	s_cbranch_execz .LBB0_141
	v_lshlrev_b64 v[138:139], 2, v[130:131]
	v_lshl_add_u64 v[140:141], s[12:13], 0, v[138:139]
	global_load_dwordx4 v[134:137], v[140:141], off
	global_load_dwordx4 v[144:147], v[140:141], off offset:64
	global_load_dwordx4 v[148:151], v[140:141], off offset:512
	global_load_dwordx4 v[152:155], v[140:141], off offset:576
	v_ashrrev_i32_e32 v143, 31, v132
	v_mad_u64_u32 v[132:133], s[30:31], v132, s27, 0
	v_mov_b32_e32 v142, v133
	v_mad_u64_u32 v[142:143], s[30:31], v143, s27, v[142:143]
	v_mov_b32_e32 v133, v142
	v_lshl_add_u64 v[132:133], v[132:133], 2, s[54:55]
	v_lshl_add_u64 v[138:139], v[132:133], 0, v[138:139]
	s_waitcnt vmcnt(0)
	v_pk_add_f32 v[136:137], v[120:121], v[136:137]
	v_pk_add_f32 v[134:135], v[118:119], v[134:135]
	global_store_dwordx4 v[138:139], v[134:137], off
	v_pk_add_f32 v[144:145], v[114:115], v[144:145]
	v_pk_add_f32 v[146:147], v[116:117], v[146:147]
	global_store_dwordx4 v[138:139], v[144:147], off offset:64
	v_pk_add_f32 v[150:151], v[96:97], v[150:151]
	v_pk_add_f32 v[148:149], v[94:95], v[148:149]
	global_store_dwordx4 v[138:139], v[148:151], off offset:512
	v_pk_add_f32 v[154:155], v[92:93], v[154:155]
	v_pk_add_f32 v[152:153], v[90:91], v[152:153]
	global_store_dwordx4 v[138:139], v[152:155], off offset:576
.LBB0_141:
	s_or_b64 exec, exec, s[42:43]
	s_nop 0
	v_or_b32_e32 v132, 32, v218
	v_cmp_lt_i32_e32 vcc, v132, v171
	s_and_saveexec_b64 s[42:43], vcc
	s_cbranch_execz .LBB0_143
	v_lshlrev_b64 v[138:139], 2, v[130:131]
	v_lshl_add_u64 v[140:141], s[12:13], 0, v[138:139]
	global_load_dwordx4 v[134:137], v[140:141], off
	global_load_dwordx4 v[144:147], v[140:141], off offset:64
	global_load_dwordx4 v[148:151], v[140:141], off offset:512
	global_load_dwordx4 v[152:155], v[140:141], off offset:576
	v_ashrrev_i32_e32 v143, 31, v132
	v_mad_u64_u32 v[132:133], s[30:31], v132, s27, 0
	v_mov_b32_e32 v142, v133
	v_mad_u64_u32 v[142:143], s[30:31], v143, s27, v[142:143]
	v_mov_b32_e32 v133, v142
	v_lshl_add_u64 v[132:133], v[132:133], 2, s[54:55]
	v_lshl_add_u64 v[138:139], v[132:133], 0, v[138:139]
	s_waitcnt vmcnt(0)
	v_pk_add_f32 v[136:137], v[104:105], v[136:137]
	v_pk_add_f32 v[134:135], v[102:103], v[134:135]
	global_store_dwordx4 v[138:139], v[134:137], off
	v_pk_add_f32 v[144:145], v[98:99], v[144:145]
	v_pk_add_f32 v[146:147], v[100:101], v[146:147]
	global_store_dwordx4 v[138:139], v[144:147], off offset:64
	v_pk_add_f32 v[150:151], v[80:81], v[150:151]
	v_pk_add_f32 v[148:149], v[78:79], v[148:149]
	global_store_dwordx4 v[138:139], v[148:151], off offset:512
	v_pk_add_f32 v[154:155], v[76:77], v[154:155]
	v_pk_add_f32 v[152:153], v[74:75], v[152:153]
	global_store_dwordx4 v[138:139], v[152:155], off offset:576
.LBB0_143:
	s_or_b64 exec, exec, s[42:43]
	s_nop 0
	v_or_b32_e32 v132, 48, v218
	v_cmp_lt_i32_e32 vcc, v132, v171
	s_and_saveexec_b64 s[42:43], vcc
	s_cbranch_execz .LBB0_145
	v_lshlrev_b64 v[138:139], 2, v[130:131]
	v_lshl_add_u64 v[140:141], s[12:13], 0, v[138:139]
	global_load_dwordx4 v[134:137], v[140:141], off
	global_load_dwordx4 v[144:147], v[140:141], off offset:64
	global_load_dwordx4 v[148:151], v[140:141], off offset:512
	global_load_dwordx4 v[152:155], v[140:141], off offset:576
	v_ashrrev_i32_e32 v143, 31, v132
	v_mad_u64_u32 v[132:133], s[30:31], v132, s27, 0
	v_mov_b32_e32 v142, v133
	v_mad_u64_u32 v[142:143], s[30:31], v143, s27, v[142:143]
	v_mov_b32_e32 v133, v142
	v_lshl_add_u64 v[132:133], v[132:133], 2, s[54:55]
	v_lshl_add_u64 v[138:139], v[132:133], 0, v[138:139]
	s_waitcnt vmcnt(0)
	v_pk_add_f32 v[136:137], v[88:89], v[136:137]
	v_pk_add_f32 v[134:135], v[86:87], v[134:135]
	global_store_dwordx4 v[138:139], v[134:137], off
	v_pk_add_f32 v[144:145], v[82:83], v[144:145]
	v_pk_add_f32 v[146:147], v[84:85], v[146:147]
	global_store_dwordx4 v[138:139], v[144:147], off offset:64
	v_pk_add_f32 v[150:151], v[72:73], v[150:151]
	v_pk_add_f32 v[148:149], v[70:71], v[148:149]
	global_store_dwordx4 v[138:139], v[148:151], off offset:512
	v_pk_add_f32 v[154:155], v[68:69], v[154:155]
	v_pk_add_f32 v[152:153], v[66:67], v[152:153]
	global_store_dwordx4 v[138:139], v[152:155], off offset:576
; DI void gemm_epilogue(const GemmJob& J, const f32x4 (&acc)[2][2][4][2], const pg8::Unit& u, int wr, int wc, int fr, int fq) {
;     ...
;     if (J.mode == 0) {
;         float* C = (float*)J.o1; const int col0 = u.pn * 256 + wc * 32 + 4 * fq;
; #pragma unroll
;         for (int ai = 0; ai < 2; ++ai)
; #pragma unroll
;             for (int m = 0; m < 4; ++m) { const int row = rloc0 + ai * 128 + m * 16;
;                 if (row < J.flag) {
; #pragma unroll
;                     for (int bj = 0; bj < 2; ++bj)
; #pragma unroll
;                         for (int n = 0; n < 2; ++n) { const int col = col0 + bj * 128 + n * 16; const f32x4 b = *(const f32x4*)(J.f1 + col);
;                             *(f32x4*)(C + (size_t)row * J.ld1 + col) = acc[ai][bj][m][n] + b; } }
;                 asm volatile("" ::: "memory"); }
.LBB0_145:
	s_or_b64 exec, exec, s[42:43]
	s_nop 0
	v_add_u32_e32 v132, 0x80, v218
	v_cmp_lt_i32_e32 vcc, v132, v171
	s_and_saveexec_b64 s[42:43], vcc
	s_cbranch_execz .LBB0_147
	v_lshlrev_b64 v[138:139], 2, v[130:131]
	v_lshl_add_u64 v[140:141], s[12:13], 0, v[138:139]
	global_load_dwordx4 v[134:137], v[140:141], off
	global_load_dwordx4 v[144:147], v[140:141], off offset:64
	global_load_dwordx4 v[148:151], v[140:141], off offset:512
	global_load_dwordx4 v[152:155], v[140:141], off offset:576
	v_ashrrev_i32_e32 v143, 31, v132
	v_mad_u64_u32 v[132:133], s[30:31], v132, s27, 0
	v_mov_b32_e32 v142, v133
	v_mad_u64_u32 v[142:143], s[30:31], v143, s27, v[142:143]
	v_mov_b32_e32 v133, v142
	v_lshl_add_u64 v[132:133], v[132:133], 2, s[54:55]
	v_lshl_add_u64 v[138:139], v[132:133], 0, v[138:139]
	s_waitcnt vmcnt(0)
	v_pk_add_f32 v[136:137], v[64:65], v[136:137]
	v_pk_add_f32 v[134:135], v[62:63], v[134:135]
	global_store_dwordx4 v[138:139], v[134:137], off
	v_pk_add_f32 v[144:145], v[58:59], v[144:145]
	v_pk_add_f32 v[146:147], v[60:61], v[146:147]
	global_store_dwordx4 v[138:139], v[144:147], off offset:64
	v_pk_add_f32 v[150:151], v[48:49], v[150:151]
	v_pk_add_f32 v[148:149], v[46:47], v[148:149]
	global_store_dwordx4 v[138:139], v[148:151], off offset:512
	v_pk_add_f32 v[154:155], v[44:45], v[154:155]
	v_pk_add_f32 v[152:153], v[42:43], v[152:153]
	global_store_dwordx4 v[138:139], v[152:155], off offset:576
.LBB0_147:
	s_or_b64 exec, exec, s[42:43]
	s_nop 0
	v_add_u32_e32 v132, 0x90, v218
	v_cmp_lt_i32_e32 vcc, v132, v171
	s_and_saveexec_b64 s[42:43], vcc
	s_cbranch_execz .LBB0_149
	v_lshlrev_b64 v[138:139], 2, v[130:131]
	v_lshl_add_u64 v[140:141], s[12:13], 0, v[138:139]
	global_load_dwordx4 v[134:137], v[140:141], off
	global_load_dwordx4 v[144:147], v[140:141], off offset:64
	global_load_dwordx4 v[148:151], v[140:141], off offset:512
	global_load_dwordx4 v[152:155], v[140:141], off offset:576
	v_ashrrev_i32_e32 v143, 31, v132
	v_mad_u64_u32 v[132:133], s[30:31], v132, s27, 0
	v_mov_b32_e32 v142, v133
	v_mad_u64_u32 v[142:143], s[30:31], v143, s27, v[142:143]
	v_mov_b32_e32 v133, v142
	v_lshl_add_u64 v[132:133], v[132:133], 2, s[54:55]
	v_lshl_add_u64 v[138:139], v[132:133], 0, v[138:139]
	s_waitcnt vmcnt(0)
	v_pk_add_f32 v[136:137], v[56:57], v[136:137]
	v_pk_add_f32 v[134:135], v[54:55], v[134:135]
	global_store_dwordx4 v[138:139], v[134:137], off
	v_pk_add_f32 v[144:145], v[50:51], v[144:145]
	v_pk_add_f32 v[146:147], v[52:53], v[146:147]
	global_store_dwordx4 v[138:139], v[144:147], off offset:64
	v_pk_add_f32 v[150:151], v[32:33], v[150:151]
	v_pk_add_f32 v[148:149], v[30:31], v[148:149]
	global_store_dwordx4 v[138:139], v[148:151], off offset:512
	v_pk_add_f32 v[154:155], v[28:29], v[154:155]
	v_pk_add_f32 v[152:153], v[26:27], v[152:153]
	global_store_dwordx4 v[138:139], v[152:155], off offset:576
.LBB0_149:
	s_or_b64 exec, exec, s[42:43]
	s_nop 0
	v_add_u32_e32 v132, 0xa0, v218
	v_cmp_lt_i32_e32 vcc, v132, v171
	s_and_saveexec_b64 s[42:43], vcc
	s_cbranch_execz .LBB0_151
	v_lshlrev_b64 v[138:139], 2, v[130:131]
	v_lshl_add_u64 v[140:141], s[12:13], 0, v[138:139]
	global_load_dwordx4 v[134:137], v[140:141], off
	global_load_dwordx4 v[144:147], v[140:141], off offset:64
	global_load_dwordx4 v[148:151], v[140:141], off offset:512
	global_load_dwordx4 v[152:155], v[140:141], off offset:576
	v_ashrrev_i32_e32 v143, 31, v132
	v_mad_u64_u32 v[132:133], s[30:31], v132, s27, 0
	v_mov_b32_e32 v142, v133
	v_mad_u64_u32 v[142:143], s[30:31], v143, s27, v[142:143]
	v_mov_b32_e32 v133, v142
	v_lshl_add_u64 v[132:133], v[132:133], 2, s[54:55]
	v_lshl_add_u64 v[138:139], v[132:133], 0, v[138:139]
	s_waitcnt vmcnt(0)
	v_pk_add_f32 v[136:137], v[40:41], v[136:137]
	v_pk_add_f32 v[134:135], v[38:39], v[134:135]
	global_store_dwordx4 v[138:139], v[134:137], off
	v_pk_add_f32 v[144:145], v[34:35], v[144:145]
	v_pk_add_f32 v[146:147], v[36:37], v[146:147]
	global_store_dwordx4 v[138:139], v[144:147], off offset:64
	v_pk_add_f32 v[150:151], v[16:17], v[150:151]
	v_pk_add_f32 v[148:149], v[14:15], v[148:149]
	global_store_dwordx4 v[138:139], v[148:151], off offset:512
	v_pk_add_f32 v[154:155], v[12:13], v[154:155]
	v_pk_add_f32 v[152:153], v[10:11], v[152:153]
	global_store_dwordx4 v[138:139], v[152:155], off offset:576
.LBB0_151:
	s_or_b64 exec, exec, s[42:43]
	s_nop 0
	v_add_u32_e32 v132, 0xb0, v218
	v_cmp_lt_i32_e32 vcc, v132, v171
	s_and_saveexec_b64 s[42:43], vcc
	s_cbranch_execz .LBB0_153
	v_lshlrev_b64 v[130:131], 2, v[130:131]
	v_lshl_add_u64 v[138:139], s[12:13], 0, v[130:131]
	global_load_dwordx4 v[134:137], v[138:139], off
	global_load_dwordx4 v[144:147], v[138:139], off offset:64
	global_load_dwordx4 v[148:151], v[138:139], off offset:512
	global_load_dwordx4 v[152:155], v[138:139], off offset:576
	v_ashrrev_i32_e32 v141, 31, v132
	v_mad_u64_u32 v[132:133], s[30:31], v132, s27, 0
	v_mov_b32_e32 v140, v133
	v_mad_u64_u32 v[140:141], s[30:31], v141, s27, v[140:141]
	v_mov_b32_e32 v133, v140
	v_lshl_add_u64 v[132:133], v[132:133], 2, s[54:55]
	v_lshl_add_u64 v[140:141], v[132:133], 0, v[130:131]
	s_waitcnt vmcnt(0)
	v_pk_add_f32 v[132:133], v[24:25], v[136:137]
	v_pk_add_f32 v[130:131], v[22:23], v[134:135]
	global_store_dwordx4 v[140:141], v[130:133], off
	v_pk_add_f32 v[146:147], v[20:21], v[146:147]
	v_pk_add_f32 v[144:145], v[18:19], v[144:145]
	global_store_dwordx4 v[140:141], v[144:147], off offset:64
	v_pk_add_f32 v[150:151], v[8:9], v[150:151]
	v_pk_add_f32 v[148:149], v[6:7], v[148:149]
	global_store_dwordx4 v[140:141], v[148:151], off offset:512
	v_pk_add_f32 v[154:155], v[4:5], v[154:155]
	v_pk_add_f32 v[152:153], v[2:3], v[152:153]
	global_store_dwordx4 v[140:141], v[152:155], off offset:576
